# hyena epilogue 0 hand-written: batched unaligned 16-byte row loads instead of uint2 + 2x ushort with per-iteration waits
# speedup vs baseline: 1.0155x; 1.0146x over previous
; DI float bf2f(unsigned v) { return __uint_as_float(v << 16); }
; DI float bflo(unsigned v) { return __uint_as_float(v << 16); }
; DI float bfhi(unsigned v) { return __uint_as_float(v & 0xffff0000u); }
; DI void sconv4(const u16* row, int t4, float w0, float w1, float w2, float bias, float (&o)[4]) {
;   const uint2 v = *(const uint2*)(row + t4);
;   const float x0 = bflo(v.x), x1 = bfhi(v.x), x2 = bflo(v.y), x3 = bfhi(v.y);
;   const float xm = (t4 > 0) ? bf2f(row[t4 - 1]) : 0.f;
;   const float xp = (t4 + 4 < SEQ) ? bf2f(row[t4 + 4]) : 0.f;
;   o[0] = w0 * xm + w1 * x0 + w2 * x1 + bias;
;   o[1] = w0 * x0 + w1 * x1 + w2 * x2 + bias;
;   o[2] = w0 * x1 + w1 * x2 + w2 * x3 + bias;
;   o[3] = w0 * x2 + w1 * x3 + w2 * xp + bias;
; }
; DI void hyena_item(const P& p, int l, int c, char* smem) {
;     ...
;   if (cwv) {
;     const float d0 = p.fbias[(size_t)(l * 2 + 0) * 512 + c];
;     const float v0 = cw[c], v1 = cw[1536 + c], v2 = cw[3072 + c], vb = cbias[c];
;     const float x0 = cw[512 + c], x1 = cw[1536 + 512 + c], x2 = cw[3072 + 512 + c], xb = cbias[512 + c];
;     const u16* rowv = p.hyT + (size_t)c * HYP + bt * SEQ;
;     const u16* rowx = p.hyT + (size_t)(512 + c) * HYP + bt * SEQ;
; #pragma unroll
;     for (int I = 0; I < 4; ++I)
; #pragma unroll
;       for (int rq = 0; rq < 4; ++rq) {
;         const int bq = 32 * I + 8 * rq + 4 * g;
;         const int t4 = 128 * a + bq;
;         float pv[4], px[4];
;         sconv4(rowv, t4, v0, v1, v2, vb, pv);
;         sconv4(rowx, t4, x0, x1, x2, xb, px);
;         float zz[4];
; #pragma unroll
;         for (int j = 0; j < 4; ++j) zz[j] = px[j] * (acc[I][4 * rq + j] * invn0 + pv[j] * d0);
;         uint2 ov; ov.x = pack2(zz[0], zz[1]); ov.y = pack2(zz[2], zz[3]);
;         *(uint2*)(U + (bt * 64 + a) * 136 + bq) = ov;
;       }
.LBB0_437:
	s_or_b64 exec, exec, s[78:79]
	v_or_b32_e32 v231, v231, v223
	v_lshrrev_b32_e32 v230, 4, v230
	v_lshlrev_b32_e32 v186, 2, v188
	v_lshlrev_b32_e32 v187, 7, v231
	v_lshlrev_b32_e32 v232, 13, v230
	v_lshlrev_b32_e32 v184, 14, v230
	v_or_b32_e32 v233, v187, v186
	s_waitcnt lgkmcnt(0)
	s_barrier
	s_and_saveexec_b64 s[78:79], s[6:7]
	s_cbranch_execz .LBB0_447
	v_readlane_b32 s88, v248, 24
	s_nop 1
	s_add_i32 s88, s72, s88
	s_mov_b32 s89, s57
	s_lshl_b64 s[88:89], s[88:89], 2
	s_add_u32 s88, s20, s88
	s_addc_u32 s89, s21, s89
	global_load_dword v239, v189, s[88:89]
	global_load_dword v240, v189, s[74:75]
	global_load_dword v241, v189, s[80:81]
	global_load_dword v242, v189, s[82:83]
	global_load_dword v243, v189, s[84:85]
	global_load_dword v247, v189, s[84:85] offset:2048
	global_load_dword v244, v189, s[74:75] offset:2048
	global_load_dword v245, v204, s[74:75]
	global_load_dword v246, v205, s[74:75] offset:2048
	s_add_u32 s100, s86, -4
	s_addc_u32 s101, s87, -1
	s_or_b32 s98, s72, 0x200
	s_mul_hi_u32 s99, s98, 0x8080
	s_mul_i32 s98, s98, 0x8080
	s_add_u32 s98, s36, s98
	s_addc_u32 s99, s37, s99
	s_add_u32 s98, s98, -4
	s_addc_u32 s99, s99, -1
	v_lshl_add_u32 v234, v233, 1, v184
	global_load_dwordx4 v[72:75], v234, s[100:101] offset:0
	global_load_dwordx4 v[76:79], v234, s[98:99] offset:0
	global_load_dwordx4 v[80:83], v234, s[100:101] offset:16
	global_load_dwordx4 v[84:87], v234, s[98:99] offset:16
	global_load_dwordx4 v[88:91], v234, s[100:101] offset:32
	global_load_dwordx4 v[92:95], v234, s[98:99] offset:32
	global_load_dwordx4 v[96:99], v234, s[100:101] offset:48
	global_load_dwordx4 v[100:103], v234, s[98:99] offset:48
	global_load_dwordx4 v[104:107], v234, s[100:101] offset:64
	global_load_dwordx4 v[108:111], v234, s[98:99] offset:64
	global_load_dwordx4 v[112:115], v234, s[100:101] offset:80
	global_load_dwordx4 v[116:119], v234, s[98:99] offset:80
	global_load_dwordx4 v[120:123], v234, s[100:101] offset:96
	global_load_dwordx4 v[124:127], v234, s[98:99] offset:96
	global_load_dwordx4 v[128:131], v234, s[100:101] offset:112
	global_load_dwordx4 v[132:135], v234, s[98:99] offset:112
	v_add_f32_e32 v238, v68, v69
	v_add_f32_e32 v238, v238, v70
	v_add_f32_e32 v238, v238, v71
	v_div_scale_f32 v169, s[88:89], v238, v238, 1.0
	v_rcp_f32_e32 v170, v169
	s_nop 0
	v_fma_f32 v171, -v169, v170, 1.0
	v_fmac_f32_e32 v170, v171, v170
	v_div_scale_f32 v171, vcc, 1.0, v238, 1.0
	v_mul_f32_e32 v236, v171, v170
	v_fma_f32 v237, -v169, v236, v171
	v_fmac_f32_e32 v236, v237, v170
	v_fma_f32 v169, -v169, v236, v171
	v_div_fmas_f32 v169, v169, v170, v236
	v_div_fixup_f32 v238, v169, v238, 1.0
	v_lshl_or_b32 v235, v230, 6, v231
	v_mul_u32_u24_e32 v235, 0x110, v235
	v_lshlrev_b32_e32 v236, 1, v186
	v_add3_u32 v235, s69, v235, v236
	s_waitcnt vmcnt(8)
	v_cmp_ne_u32_e32 vcc, 0, v233
	s_nop 1
	v_and_b32_e32 v168, 0xffff0000, v72
	v_cndmask_b32_e32 v168, 0, v168, vcc
	v_lshlrev_b32_e32 v169, 16, v73
	v_and_b32_e32 v170, 0xffff0000, v73
	v_lshlrev_b32_e32 v171, 16, v74
	v_and_b32_e32 v172, 0xffff0000, v74
	v_lshlrev_b32_e32 v173, 16, v75
	v_mul_f32_e32 v174, v240, v168
	v_fmac_f32_e32 v174, v241, v169
	v_fmac_f32_e32 v174, v242, v170
	v_add_f32_e32 v174, v243, v174
	v_mul_f32_e32 v175, v240, v169
	v_fmac_f32_e32 v175, v241, v170
	v_fmac_f32_e32 v175, v242, v171
	v_add_f32_e32 v175, v243, v175
	v_mul_f32_e32 v176, v240, v170
	v_fmac_f32_e32 v176, v241, v171
	v_fmac_f32_e32 v176, v242, v172
	v_add_f32_e32 v176, v243, v176
	v_mul_f32_e32 v177, v240, v171
	v_fmac_f32_e32 v177, v241, v172
	v_fmac_f32_e32 v177, v242, v173
	v_add_f32_e32 v177, v243, v177
	v_mul_f32_e32 v174, v239, v174
	v_mul_f32_e32 v175, v239, v175
	v_mul_f32_e32 v176, v239, v176
	v_mul_f32_e32 v177, v239, v177
	v_fmac_f32_e32 v174, v238, v48
	v_fmac_f32_e32 v175, v238, v49
	v_fmac_f32_e32 v176, v238, v50
	v_fmac_f32_e32 v177, v238, v51
	v_and_b32_e32 v168, 0xffff0000, v76
	v_cndmask_b32_e32 v168, 0, v168, vcc
	v_lshlrev_b32_e32 v169, 16, v77
	v_and_b32_e32 v170, 0xffff0000, v77
	v_lshlrev_b32_e32 v171, 16, v78
	v_and_b32_e32 v172, 0xffff0000, v78
	v_lshlrev_b32_e32 v173, 16, v79
	v_mul_f32_e32 v178, v244, v168
	v_fmac_f32_e32 v178, v245, v169
	v_fmac_f32_e32 v178, v246, v170
	v_add_f32_e32 v178, v247, v178
	v_mul_f32_e32 v179, v244, v169
	v_fmac_f32_e32 v179, v245, v170
	v_fmac_f32_e32 v179, v246, v171
	v_add_f32_e32 v179, v247, v179
	v_mul_f32_e32 v180, v244, v170
	v_fmac_f32_e32 v180, v245, v171
	v_fmac_f32_e32 v180, v246, v172
	v_add_f32_e32 v180, v247, v180
	v_mul_f32_e32 v181, v244, v171
	v_fmac_f32_e32 v181, v245, v172
	v_fmac_f32_e32 v181, v246, v173
	v_add_f32_e32 v181, v247, v181
	v_mul_f32_e32 v174, v174, v178
	v_mul_f32_e32 v175, v175, v179
	v_mul_f32_e32 v176, v176, v180
	v_mul_f32_e32 v177, v177, v181
	v_cvt_pk_bf16_f32 v182, v174, v175
	v_cvt_pk_bf16_f32 v183, v176, v177
	ds_write_b64 v235, v[182:183] offset:0
	v_and_b32_e32 v168, 0xffff0000, v80
	v_lshlrev_b32_e32 v169, 16, v81
	v_and_b32_e32 v170, 0xffff0000, v81
	v_lshlrev_b32_e32 v171, 16, v82
	v_and_b32_e32 v172, 0xffff0000, v82
	v_lshlrev_b32_e32 v173, 16, v83
	v_mul_f32_e32 v174, v240, v168
	v_fmac_f32_e32 v174, v241, v169
	v_fmac_f32_e32 v174, v242, v170
	v_add_f32_e32 v174, v243, v174
	v_mul_f32_e32 v175, v240, v169
	v_fmac_f32_e32 v175, v241, v170
	v_fmac_f32_e32 v175, v242, v171
	v_add_f32_e32 v175, v243, v175
	v_mul_f32_e32 v176, v240, v170
	v_fmac_f32_e32 v176, v241, v171
	v_fmac_f32_e32 v176, v242, v172
	v_add_f32_e32 v176, v243, v176
	v_mul_f32_e32 v177, v240, v171
	v_fmac_f32_e32 v177, v241, v172
	v_fmac_f32_e32 v177, v242, v173
	v_add_f32_e32 v177, v243, v177
	v_mul_f32_e32 v174, v239, v174
; DI void hyena_item(const P& p, int l, int c, char* smem) {
;     ...
;   if (cwv) {
;     const float d0 = p.fbias[(size_t)(l * 2 + 0) * 512 + c];
;     const float v0 = cw[c], v1 = cw[1536 + c], v2 = cw[3072 + c], vb = cbias[c];
;     const float x0 = cw[512 + c], x1 = cw[1536 + 512 + c], x2 = cw[3072 + 512 + c], xb = cbias[512 + c];
;     const u16* rowv = p.hyT + (size_t)c * HYP + bt * SEQ;
;     const u16* rowx = p.hyT + (size_t)(512 + c) * HYP + bt * SEQ;
; #pragma unroll
;     for (int I = 0; I < 4; ++I)
; #pragma unroll
;       for (int rq = 0; rq < 4; ++rq) {
;         const int bq = 32 * I + 8 * rq + 4 * g;
;         const int t4 = 128 * a + bq;
;         float pv[4], px[4];
;         sconv4(rowv, t4, v0, v1, v2, vb, pv);
;         sconv4(rowx, t4, x0, x1, x2, xb, px);
;         float zz[4];
; #pragma unroll
;         for (int j = 0; j < 4; ++j) zz[j] = px[j] * (acc[I][4 * rq + j] * invn0 + pv[j] * d0);
;         uint2 ov; ov.x = pack2(zz[0], zz[1]); ov.y = pack2(zz[2], zz[3]);
;         *(uint2*)(U + (bt * 64 + a) * 136 + bq) = ov;
;       }
	v_mul_f32_e32 v175, v239, v175
	v_mul_f32_e32 v176, v239, v176
	v_mul_f32_e32 v177, v239, v177
	v_fmac_f32_e32 v174, v238, v52
	v_fmac_f32_e32 v175, v238, v53
	v_fmac_f32_e32 v176, v238, v54
	v_fmac_f32_e32 v177, v238, v55
	v_and_b32_e32 v168, 0xffff0000, v84
	v_lshlrev_b32_e32 v169, 16, v85
	v_and_b32_e32 v170, 0xffff0000, v85
	v_lshlrev_b32_e32 v171, 16, v86
	v_and_b32_e32 v172, 0xffff0000, v86
	v_lshlrev_b32_e32 v173, 16, v87
	v_mul_f32_e32 v178, v244, v168
	v_fmac_f32_e32 v178, v245, v169
	v_fmac_f32_e32 v178, v246, v170
	v_add_f32_e32 v178, v247, v178
	v_mul_f32_e32 v179, v244, v169
	v_fmac_f32_e32 v179, v245, v170
	v_fmac_f32_e32 v179, v246, v171
	v_add_f32_e32 v179, v247, v179
	v_mul_f32_e32 v180, v244, v170
	v_fmac_f32_e32 v180, v245, v171
	v_fmac_f32_e32 v180, v246, v172
	v_add_f32_e32 v180, v247, v180
	v_mul_f32_e32 v181, v244, v171
	v_fmac_f32_e32 v181, v245, v172
	v_fmac_f32_e32 v181, v246, v173
	v_add_f32_e32 v181, v247, v181
	v_mul_f32_e32 v174, v174, v178
	v_mul_f32_e32 v175, v175, v179
	v_mul_f32_e32 v176, v176, v180
	v_mul_f32_e32 v177, v177, v181
	v_cvt_pk_bf16_f32 v182, v174, v175
	v_cvt_pk_bf16_f32 v183, v176, v177
	ds_write_b64 v235, v[182:183] offset:16
	v_and_b32_e32 v168, 0xffff0000, v88
	v_lshlrev_b32_e32 v169, 16, v89
	v_and_b32_e32 v170, 0xffff0000, v89
	v_lshlrev_b32_e32 v171, 16, v90
	v_and_b32_e32 v172, 0xffff0000, v90
	v_lshlrev_b32_e32 v173, 16, v91
	v_mul_f32_e32 v174, v240, v168
	v_fmac_f32_e32 v174, v241, v169
	v_fmac_f32_e32 v174, v242, v170
	v_add_f32_e32 v174, v243, v174
	v_mul_f32_e32 v175, v240, v169
	v_fmac_f32_e32 v175, v241, v170
	v_fmac_f32_e32 v175, v242, v171
	v_add_f32_e32 v175, v243, v175
	v_mul_f32_e32 v176, v240, v170
	v_fmac_f32_e32 v176, v241, v171
	v_fmac_f32_e32 v176, v242, v172
	v_add_f32_e32 v176, v243, v176
	v_mul_f32_e32 v177, v240, v171
	v_fmac_f32_e32 v177, v241, v172
	v_fmac_f32_e32 v177, v242, v173
	v_add_f32_e32 v177, v243, v177
	v_mul_f32_e32 v174, v239, v174
	v_mul_f32_e32 v175, v239, v175
	v_mul_f32_e32 v176, v239, v176
	v_mul_f32_e32 v177, v239, v177
	v_fmac_f32_e32 v174, v238, v56
	v_fmac_f32_e32 v175, v238, v57
	v_fmac_f32_e32 v176, v238, v58
	v_fmac_f32_e32 v177, v238, v59
	v_and_b32_e32 v168, 0xffff0000, v92
	v_lshlrev_b32_e32 v169, 16, v93
	v_and_b32_e32 v170, 0xffff0000, v93
	v_lshlrev_b32_e32 v171, 16, v94
	v_and_b32_e32 v172, 0xffff0000, v94
	v_lshlrev_b32_e32 v173, 16, v95
	v_mul_f32_e32 v178, v244, v168
	v_fmac_f32_e32 v178, v245, v169
	v_fmac_f32_e32 v178, v246, v170
	v_add_f32_e32 v178, v247, v178
	v_mul_f32_e32 v179, v244, v169
	v_fmac_f32_e32 v179, v245, v170
	v_fmac_f32_e32 v179, v246, v171
	v_add_f32_e32 v179, v247, v179
	v_mul_f32_e32 v180, v244, v170
	v_fmac_f32_e32 v180, v245, v171
	v_fmac_f32_e32 v180, v246, v172
	v_add_f32_e32 v180, v247, v180
	v_mul_f32_e32 v181, v244, v171
	v_fmac_f32_e32 v181, v245, v172
	v_fmac_f32_e32 v181, v246, v173
	v_add_f32_e32 v181, v247, v181
	v_mul_f32_e32 v174, v174, v178
	v_mul_f32_e32 v175, v175, v179
	v_mul_f32_e32 v176, v176, v180
	v_mul_f32_e32 v177, v177, v181
	v_cvt_pk_bf16_f32 v182, v174, v175
	v_cvt_pk_bf16_f32 v183, v176, v177
	ds_write_b64 v235, v[182:183] offset:32
	v_and_b32_e32 v168, 0xffff0000, v96
	v_lshlrev_b32_e32 v169, 16, v97
	v_and_b32_e32 v170, 0xffff0000, v97
	v_lshlrev_b32_e32 v171, 16, v98
	v_and_b32_e32 v172, 0xffff0000, v98
	v_lshlrev_b32_e32 v173, 16, v99
	v_mul_f32_e32 v174, v240, v168
	v_fmac_f32_e32 v174, v241, v169
	v_fmac_f32_e32 v174, v242, v170
	v_add_f32_e32 v174, v243, v174
	v_mul_f32_e32 v175, v240, v169
	v_fmac_f32_e32 v175, v241, v170
	v_fmac_f32_e32 v175, v242, v171
	v_add_f32_e32 v175, v243, v175
	v_mul_f32_e32 v176, v240, v170
	v_fmac_f32_e32 v176, v241, v171
	v_fmac_f32_e32 v176, v242, v172
	v_add_f32_e32 v176, v243, v176
	v_mul_f32_e32 v177, v240, v171
	v_fmac_f32_e32 v177, v241, v172
	v_fmac_f32_e32 v177, v242, v173
	v_add_f32_e32 v177, v243, v177
	v_mul_f32_e32 v174, v239, v174
	v_mul_f32_e32 v175, v239, v175
	v_mul_f32_e32 v176, v239, v176
	v_mul_f32_e32 v177, v239, v177
	v_fmac_f32_e32 v174, v238, v60
	v_fmac_f32_e32 v175, v238, v61
	v_fmac_f32_e32 v176, v238, v62
	v_fmac_f32_e32 v177, v238, v63
	v_and_b32_e32 v168, 0xffff0000, v100
	v_lshlrev_b32_e32 v169, 16, v101
	v_and_b32_e32 v170, 0xffff0000, v101
	v_lshlrev_b32_e32 v171, 16, v102
	v_and_b32_e32 v172, 0xffff0000, v102
	v_lshlrev_b32_e32 v173, 16, v103
	v_mul_f32_e32 v178, v244, v168
	v_fmac_f32_e32 v178, v245, v169
	v_fmac_f32_e32 v178, v246, v170
	v_add_f32_e32 v178, v247, v178
	v_mul_f32_e32 v179, v244, v169
	v_fmac_f32_e32 v179, v245, v170
	v_fmac_f32_e32 v179, v246, v171
	v_add_f32_e32 v179, v247, v179
	v_mul_f32_e32 v180, v244, v170
	v_fmac_f32_e32 v180, v245, v171
	v_fmac_f32_e32 v180, v246, v172
	v_add_f32_e32 v180, v247, v180
	v_mul_f32_e32 v181, v244, v171
	v_fmac_f32_e32 v181, v245, v172
	v_fmac_f32_e32 v181, v246, v173
	v_add_f32_e32 v181, v247, v181
	v_mul_f32_e32 v174, v174, v178
	v_mul_f32_e32 v175, v175, v179
	v_mul_f32_e32 v176, v176, v180
	v_mul_f32_e32 v177, v177, v181
	v_cvt_pk_bf16_f32 v182, v174, v175
	v_cvt_pk_bf16_f32 v183, v176, v177
	ds_write_b64 v235, v[182:183] offset:48
	global_load_dwordx4 v[136:139], v234, s[100:101] offset:128
	global_load_dwordx4 v[140:143], v234, s[98:99] offset:128
	global_load_dwordx4 v[144:147], v234, s[100:101] offset:144
	global_load_dwordx4 v[148:151], v234, s[98:99] offset:144
	global_load_dwordx4 v[152:155], v234, s[100:101] offset:160
	global_load_dwordx4 v[156:159], v234, s[98:99] offset:160
	global_load_dwordx4 v[160:163], v234, s[100:101] offset:176
	global_load_dwordx4 v[164:167], v234, s[98:99] offset:176
	s_waitcnt vmcnt(8)
; DI void hyena_item(const P& p, int l, int c, char* smem) {
;     ...
;   if (cwv) {
;     const float d0 = p.fbias[(size_t)(l * 2 + 0) * 512 + c];
;     const float v0 = cw[c], v1 = cw[1536 + c], v2 = cw[3072 + c], vb = cbias[c];
;     const float x0 = cw[512 + c], x1 = cw[1536 + 512 + c], x2 = cw[3072 + 512 + c], xb = cbias[512 + c];
;     const u16* rowv = p.hyT + (size_t)c * HYP + bt * SEQ;
;     const u16* rowx = p.hyT + (size_t)(512 + c) * HYP + bt * SEQ;
; #pragma unroll
;     for (int I = 0; I < 4; ++I)
; #pragma unroll
;       for (int rq = 0; rq < 4; ++rq) {
;         const int bq = 32 * I + 8 * rq + 4 * g;
;         const int t4 = 128 * a + bq;
;         float pv[4], px[4];
;         sconv4(rowv, t4, v0, v1, v2, vb, pv);
;         sconv4(rowx, t4, x0, x1, x2, xb, px);
;         float zz[4];
; #pragma unroll
;         for (int j = 0; j < 4; ++j) zz[j] = px[j] * (acc[I][4 * rq + j] * invn0 + pv[j] * d0);
;         uint2 ov; ov.x = pack2(zz[0], zz[1]); ov.y = pack2(zz[2], zz[3]);
;         *(uint2*)(U + (bt * 64 + a) * 136 + bq) = ov;
;       }
	v_and_b32_e32 v168, 0xffff0000, v104
	v_lshlrev_b32_e32 v169, 16, v105
	v_and_b32_e32 v170, 0xffff0000, v105
	v_lshlrev_b32_e32 v171, 16, v106
	v_and_b32_e32 v172, 0xffff0000, v106
	v_lshlrev_b32_e32 v173, 16, v107
	v_mul_f32_e32 v174, v240, v168
	v_fmac_f32_e32 v174, v241, v169
	v_fmac_f32_e32 v174, v242, v170
	v_add_f32_e32 v174, v243, v174
	v_mul_f32_e32 v175, v240, v169
	v_fmac_f32_e32 v175, v241, v170
	v_fmac_f32_e32 v175, v242, v171
	v_add_f32_e32 v175, v243, v175
	v_mul_f32_e32 v176, v240, v170
	v_fmac_f32_e32 v176, v241, v171
	v_fmac_f32_e32 v176, v242, v172
	v_add_f32_e32 v176, v243, v176
	v_mul_f32_e32 v177, v240, v171
	v_fmac_f32_e32 v177, v241, v172
	v_fmac_f32_e32 v177, v242, v173
	v_add_f32_e32 v177, v243, v177
	v_mul_f32_e32 v174, v239, v174
	v_mul_f32_e32 v175, v239, v175
	v_mul_f32_e32 v176, v239, v176
	v_mul_f32_e32 v177, v239, v177
	v_fmac_f32_e32 v174, v238, v32
	v_fmac_f32_e32 v175, v238, v33
	v_fmac_f32_e32 v176, v238, v34
	v_fmac_f32_e32 v177, v238, v35
	v_and_b32_e32 v168, 0xffff0000, v108
	v_lshlrev_b32_e32 v169, 16, v109
	v_and_b32_e32 v170, 0xffff0000, v109
	v_lshlrev_b32_e32 v171, 16, v110
	v_and_b32_e32 v172, 0xffff0000, v110
	v_lshlrev_b32_e32 v173, 16, v111
	v_mul_f32_e32 v178, v244, v168
	v_fmac_f32_e32 v178, v245, v169
	v_fmac_f32_e32 v178, v246, v170
	v_add_f32_e32 v178, v247, v178
	v_mul_f32_e32 v179, v244, v169
	v_fmac_f32_e32 v179, v245, v170
	v_fmac_f32_e32 v179, v246, v171
	v_add_f32_e32 v179, v247, v179
	v_mul_f32_e32 v180, v244, v170
	v_fmac_f32_e32 v180, v245, v171
	v_fmac_f32_e32 v180, v246, v172
	v_add_f32_e32 v180, v247, v180
	v_mul_f32_e32 v181, v244, v171
	v_fmac_f32_e32 v181, v245, v172
	v_fmac_f32_e32 v181, v246, v173
	v_add_f32_e32 v181, v247, v181
	v_mul_f32_e32 v174, v174, v178
	v_mul_f32_e32 v175, v175, v179
	v_mul_f32_e32 v176, v176, v180
	v_mul_f32_e32 v177, v177, v181
	v_cvt_pk_bf16_f32 v182, v174, v175
	v_cvt_pk_bf16_f32 v183, v176, v177
	ds_write_b64 v235, v[182:183] offset:64
	v_and_b32_e32 v168, 0xffff0000, v112
	v_lshlrev_b32_e32 v169, 16, v113
	v_and_b32_e32 v170, 0xffff0000, v113
	v_lshlrev_b32_e32 v171, 16, v114
	v_and_b32_e32 v172, 0xffff0000, v114
	v_lshlrev_b32_e32 v173, 16, v115
	v_mul_f32_e32 v174, v240, v168
	v_fmac_f32_e32 v174, v241, v169
	v_fmac_f32_e32 v174, v242, v170
	v_add_f32_e32 v174, v243, v174
	v_mul_f32_e32 v175, v240, v169
	v_fmac_f32_e32 v175, v241, v170
	v_fmac_f32_e32 v175, v242, v171
	v_add_f32_e32 v175, v243, v175
	v_mul_f32_e32 v176, v240, v170
	v_fmac_f32_e32 v176, v241, v171
	v_fmac_f32_e32 v176, v242, v172
	v_add_f32_e32 v176, v243, v176
	v_mul_f32_e32 v177, v240, v171
	v_fmac_f32_e32 v177, v241, v172
	v_fmac_f32_e32 v177, v242, v173
	v_add_f32_e32 v177, v243, v177
	v_mul_f32_e32 v174, v239, v174
	v_mul_f32_e32 v175, v239, v175
	v_mul_f32_e32 v176, v239, v176
	v_mul_f32_e32 v177, v239, v177
	v_fmac_f32_e32 v174, v238, v36
	v_fmac_f32_e32 v175, v238, v37
	v_fmac_f32_e32 v176, v238, v38
	v_fmac_f32_e32 v177, v238, v39
	v_and_b32_e32 v168, 0xffff0000, v116
	v_lshlrev_b32_e32 v169, 16, v117
	v_and_b32_e32 v170, 0xffff0000, v117
	v_lshlrev_b32_e32 v171, 16, v118
	v_and_b32_e32 v172, 0xffff0000, v118
	v_lshlrev_b32_e32 v173, 16, v119
	v_mul_f32_e32 v178, v244, v168
	v_fmac_f32_e32 v178, v245, v169
	v_fmac_f32_e32 v178, v246, v170
	v_add_f32_e32 v178, v247, v178
	v_mul_f32_e32 v179, v244, v169
	v_fmac_f32_e32 v179, v245, v170
	v_fmac_f32_e32 v179, v246, v171
	v_add_f32_e32 v179, v247, v179
	v_mul_f32_e32 v180, v244, v170
	v_fmac_f32_e32 v180, v245, v171
	v_fmac_f32_e32 v180, v246, v172
	v_add_f32_e32 v180, v247, v180
	v_mul_f32_e32 v181, v244, v171
	v_fmac_f32_e32 v181, v245, v172
	v_fmac_f32_e32 v181, v246, v173
	v_add_f32_e32 v181, v247, v181
	v_mul_f32_e32 v174, v174, v178
	v_mul_f32_e32 v175, v175, v179
	v_mul_f32_e32 v176, v176, v180
	v_mul_f32_e32 v177, v177, v181
	v_cvt_pk_bf16_f32 v182, v174, v175
	v_cvt_pk_bf16_f32 v183, v176, v177
	ds_write_b64 v235, v[182:183] offset:80
	v_and_b32_e32 v168, 0xffff0000, v120
	v_lshlrev_b32_e32 v169, 16, v121
	v_and_b32_e32 v170, 0xffff0000, v121
	v_lshlrev_b32_e32 v171, 16, v122
	v_and_b32_e32 v172, 0xffff0000, v122
	v_lshlrev_b32_e32 v173, 16, v123
	v_mul_f32_e32 v174, v240, v168
	v_fmac_f32_e32 v174, v241, v169
	v_fmac_f32_e32 v174, v242, v170
	v_add_f32_e32 v174, v243, v174
	v_mul_f32_e32 v175, v240, v169
	v_fmac_f32_e32 v175, v241, v170
	v_fmac_f32_e32 v175, v242, v171
	v_add_f32_e32 v175, v243, v175
	v_mul_f32_e32 v176, v240, v170
	v_fmac_f32_e32 v176, v241, v171
	v_fmac_f32_e32 v176, v242, v172
	v_add_f32_e32 v176, v243, v176
	v_mul_f32_e32 v177, v240, v171
	v_fmac_f32_e32 v177, v241, v172
	v_fmac_f32_e32 v177, v242, v173
	v_add_f32_e32 v177, v243, v177
	v_mul_f32_e32 v174, v239, v174
	v_mul_f32_e32 v175, v239, v175
	v_mul_f32_e32 v176, v239, v176
	v_mul_f32_e32 v177, v239, v177
	v_fmac_f32_e32 v174, v238, v40
	v_fmac_f32_e32 v175, v238, v41
	v_fmac_f32_e32 v176, v238, v42
	v_fmac_f32_e32 v177, v238, v43
	v_and_b32_e32 v168, 0xffff0000, v124
	v_lshlrev_b32_e32 v169, 16, v125
	v_and_b32_e32 v170, 0xffff0000, v125
	v_lshlrev_b32_e32 v171, 16, v126
	v_and_b32_e32 v172, 0xffff0000, v126
	v_lshlrev_b32_e32 v173, 16, v127
	v_mul_f32_e32 v178, v244, v168
	v_fmac_f32_e32 v178, v245, v169
	v_fmac_f32_e32 v178, v246, v170
	v_add_f32_e32 v178, v247, v178
	v_mul_f32_e32 v179, v244, v169
	v_fmac_f32_e32 v179, v245, v170
	v_fmac_f32_e32 v179, v246, v171
	v_add_f32_e32 v179, v247, v179
	v_mul_f32_e32 v180, v244, v170
	v_fmac_f32_e32 v180, v245, v171
	v_fmac_f32_e32 v180, v246, v172
	v_add_f32_e32 v180, v247, v180
	v_mul_f32_e32 v181, v244, v171
	v_fmac_f32_e32 v181, v245, v172
	v_fmac_f32_e32 v181, v246, v173
; DI void hyena_item(const P& p, int l, int c, char* smem) {
;     ...
;   if (cwv) {
;     const float d0 = p.fbias[(size_t)(l * 2 + 0) * 512 + c];
;     const float v0 = cw[c], v1 = cw[1536 + c], v2 = cw[3072 + c], vb = cbias[c];
;     const float x0 = cw[512 + c], x1 = cw[1536 + 512 + c], x2 = cw[3072 + 512 + c], xb = cbias[512 + c];
;     const u16* rowv = p.hyT + (size_t)c * HYP + bt * SEQ;
;     const u16* rowx = p.hyT + (size_t)(512 + c) * HYP + bt * SEQ;
; #pragma unroll
;     for (int I = 0; I < 4; ++I)
; #pragma unroll
;       for (int rq = 0; rq < 4; ++rq) {
;         const int bq = 32 * I + 8 * rq + 4 * g;
;         const int t4 = 128 * a + bq;
;         float pv[4], px[4];
;         sconv4(rowv, t4, v0, v1, v2, vb, pv);
;         sconv4(rowx, t4, x0, x1, x2, xb, px);
;         float zz[4];
; #pragma unroll
;         for (int j = 0; j < 4; ++j) zz[j] = px[j] * (acc[I][4 * rq + j] * invn0 + pv[j] * d0);
;         uint2 ov; ov.x = pack2(zz[0], zz[1]); ov.y = pack2(zz[2], zz[3]);
;         *(uint2*)(U + (bt * 64 + a) * 136 + bq) = ov;
;       }
	v_add_f32_e32 v181, v247, v181
	v_mul_f32_e32 v174, v174, v178
	v_mul_f32_e32 v175, v175, v179
	v_mul_f32_e32 v176, v176, v180
	v_mul_f32_e32 v177, v177, v181
	v_cvt_pk_bf16_f32 v182, v174, v175
	v_cvt_pk_bf16_f32 v183, v176, v177
	ds_write_b64 v235, v[182:183] offset:96
	v_and_b32_e32 v168, 0xffff0000, v128
	v_lshlrev_b32_e32 v169, 16, v129
	v_and_b32_e32 v170, 0xffff0000, v129
	v_lshlrev_b32_e32 v171, 16, v130
	v_and_b32_e32 v172, 0xffff0000, v130
	v_lshlrev_b32_e32 v173, 16, v131
	v_mul_f32_e32 v174, v240, v168
	v_fmac_f32_e32 v174, v241, v169
	v_fmac_f32_e32 v174, v242, v170
	v_add_f32_e32 v174, v243, v174
	v_mul_f32_e32 v175, v240, v169
	v_fmac_f32_e32 v175, v241, v170
	v_fmac_f32_e32 v175, v242, v171
	v_add_f32_e32 v175, v243, v175
	v_mul_f32_e32 v176, v240, v170
	v_fmac_f32_e32 v176, v241, v171
	v_fmac_f32_e32 v176, v242, v172
	v_add_f32_e32 v176, v243, v176
	v_mul_f32_e32 v177, v240, v171
	v_fmac_f32_e32 v177, v241, v172
	v_fmac_f32_e32 v177, v242, v173
	v_add_f32_e32 v177, v243, v177
	v_mul_f32_e32 v174, v239, v174
	v_mul_f32_e32 v175, v239, v175
	v_mul_f32_e32 v176, v239, v176
	v_mul_f32_e32 v177, v239, v177
	v_fmac_f32_e32 v174, v238, v44
	v_fmac_f32_e32 v175, v238, v45
	v_fmac_f32_e32 v176, v238, v46
	v_fmac_f32_e32 v177, v238, v47
	v_and_b32_e32 v168, 0xffff0000, v132
	v_lshlrev_b32_e32 v169, 16, v133
	v_and_b32_e32 v170, 0xffff0000, v133
	v_lshlrev_b32_e32 v171, 16, v134
	v_and_b32_e32 v172, 0xffff0000, v134
	v_lshlrev_b32_e32 v173, 16, v135
	v_mul_f32_e32 v178, v244, v168
	v_fmac_f32_e32 v178, v245, v169
	v_fmac_f32_e32 v178, v246, v170
	v_add_f32_e32 v178, v247, v178
	v_mul_f32_e32 v179, v244, v169
	v_fmac_f32_e32 v179, v245, v170
	v_fmac_f32_e32 v179, v246, v171
	v_add_f32_e32 v179, v247, v179
	v_mul_f32_e32 v180, v244, v170
	v_fmac_f32_e32 v180, v245, v171
	v_fmac_f32_e32 v180, v246, v172
	v_add_f32_e32 v180, v247, v180
	v_mul_f32_e32 v181, v244, v171
	v_fmac_f32_e32 v181, v245, v172
	v_fmac_f32_e32 v181, v246, v173
	v_add_f32_e32 v181, v247, v181
	v_mul_f32_e32 v174, v174, v178
	v_mul_f32_e32 v175, v175, v179
	v_mul_f32_e32 v176, v176, v180
	v_mul_f32_e32 v177, v177, v181
	v_cvt_pk_bf16_f32 v182, v174, v175
	v_cvt_pk_bf16_f32 v183, v176, v177
	ds_write_b64 v235, v[182:183] offset:112
	global_load_dwordx4 v[72:75], v234, s[100:101] offset:192
	global_load_dwordx4 v[76:79], v234, s[98:99] offset:192
	global_load_dwordx4 v[80:83], v234, s[100:101] offset:208
	global_load_dwordx4 v[84:87], v234, s[98:99] offset:208
	global_load_dwordx4 v[88:91], v234, s[100:101] offset:224
	global_load_dwordx4 v[92:95], v234, s[98:99] offset:224
	global_load_dwordx4 v[96:99], v234, s[100:101] offset:240
	global_load_dwordx4 v[100:103], v234, s[98:99] offset:240
	s_waitcnt vmcnt(8)
	v_and_b32_e32 v168, 0xffff0000, v136
	v_lshlrev_b32_e32 v169, 16, v137
	v_and_b32_e32 v170, 0xffff0000, v137
	v_lshlrev_b32_e32 v171, 16, v138
	v_and_b32_e32 v172, 0xffff0000, v138
	v_lshlrev_b32_e32 v173, 16, v139
	v_mul_f32_e32 v174, v240, v168
	v_fmac_f32_e32 v174, v241, v169
	v_fmac_f32_e32 v174, v242, v170
	v_add_f32_e32 v174, v243, v174
	v_mul_f32_e32 v175, v240, v169
	v_fmac_f32_e32 v175, v241, v170
	v_fmac_f32_e32 v175, v242, v171
	v_add_f32_e32 v175, v243, v175
	v_mul_f32_e32 v176, v240, v170
	v_fmac_f32_e32 v176, v241, v171
	v_fmac_f32_e32 v176, v242, v172
	v_add_f32_e32 v176, v243, v176
	v_mul_f32_e32 v177, v240, v171
	v_fmac_f32_e32 v177, v241, v172
	v_fmac_f32_e32 v177, v242, v173
	v_add_f32_e32 v177, v243, v177
	v_mul_f32_e32 v174, v239, v174
	v_mul_f32_e32 v175, v239, v175
	v_mul_f32_e32 v176, v239, v176
	v_mul_f32_e32 v177, v239, v177
	v_fmac_f32_e32 v174, v238, v16
	v_fmac_f32_e32 v175, v238, v17
	v_fmac_f32_e32 v176, v238, v18
	v_fmac_f32_e32 v177, v238, v19
	v_and_b32_e32 v168, 0xffff0000, v140
	v_lshlrev_b32_e32 v169, 16, v141
	v_and_b32_e32 v170, 0xffff0000, v141
	v_lshlrev_b32_e32 v171, 16, v142
	v_and_b32_e32 v172, 0xffff0000, v142
	v_lshlrev_b32_e32 v173, 16, v143
	v_mul_f32_e32 v178, v244, v168
	v_fmac_f32_e32 v178, v245, v169
	v_fmac_f32_e32 v178, v246, v170
	v_add_f32_e32 v178, v247, v178
	v_mul_f32_e32 v179, v244, v169
	v_fmac_f32_e32 v179, v245, v170
	v_fmac_f32_e32 v179, v246, v171
	v_add_f32_e32 v179, v247, v179
	v_mul_f32_e32 v180, v244, v170
	v_fmac_f32_e32 v180, v245, v171
	v_fmac_f32_e32 v180, v246, v172
	v_add_f32_e32 v180, v247, v180
	v_mul_f32_e32 v181, v244, v171
	v_fmac_f32_e32 v181, v245, v172
	v_fmac_f32_e32 v181, v246, v173
	v_add_f32_e32 v181, v247, v181
	v_mul_f32_e32 v174, v174, v178
	v_mul_f32_e32 v175, v175, v179
	v_mul_f32_e32 v176, v176, v180
	v_mul_f32_e32 v177, v177, v181
	v_cvt_pk_bf16_f32 v182, v174, v175
	v_cvt_pk_bf16_f32 v183, v176, v177
	ds_write_b64 v235, v[182:183] offset:128
	v_and_b32_e32 v168, 0xffff0000, v144
	v_lshlrev_b32_e32 v169, 16, v145
	v_and_b32_e32 v170, 0xffff0000, v145
	v_lshlrev_b32_e32 v171, 16, v146
	v_and_b32_e32 v172, 0xffff0000, v146
	v_lshlrev_b32_e32 v173, 16, v147
	v_mul_f32_e32 v174, v240, v168
	v_fmac_f32_e32 v174, v241, v169
	v_fmac_f32_e32 v174, v242, v170
	v_add_f32_e32 v174, v243, v174
	v_mul_f32_e32 v175, v240, v169
	v_fmac_f32_e32 v175, v241, v170
	v_fmac_f32_e32 v175, v242, v171
	v_add_f32_e32 v175, v243, v175
	v_mul_f32_e32 v176, v240, v170
	v_fmac_f32_e32 v176, v241, v171
	v_fmac_f32_e32 v176, v242, v172
	v_add_f32_e32 v176, v243, v176
	v_mul_f32_e32 v177, v240, v171
	v_fmac_f32_e32 v177, v241, v172
	v_fmac_f32_e32 v177, v242, v173
	v_add_f32_e32 v177, v243, v177
	v_mul_f32_e32 v174, v239, v174
	v_mul_f32_e32 v175, v239, v175
	v_mul_f32_e32 v176, v239, v176
	v_mul_f32_e32 v177, v239, v177
	v_fmac_f32_e32 v174, v238, v20
	v_fmac_f32_e32 v175, v238, v21
; DI void hyena_item(const P& p, int l, int c, char* smem) {
;     ...
;   if (cwv) {
;     const float d0 = p.fbias[(size_t)(l * 2 + 0) * 512 + c];
;     const float v0 = cw[c], v1 = cw[1536 + c], v2 = cw[3072 + c], vb = cbias[c];
;     const float x0 = cw[512 + c], x1 = cw[1536 + 512 + c], x2 = cw[3072 + 512 + c], xb = cbias[512 + c];
;     const u16* rowv = p.hyT + (size_t)c * HYP + bt * SEQ;
;     const u16* rowx = p.hyT + (size_t)(512 + c) * HYP + bt * SEQ;
; #pragma unroll
;     for (int I = 0; I < 4; ++I)
; #pragma unroll
;       for (int rq = 0; rq < 4; ++rq) {
;         const int bq = 32 * I + 8 * rq + 4 * g;
;         const int t4 = 128 * a + bq;
;         float pv[4], px[4];
;         sconv4(rowv, t4, v0, v1, v2, vb, pv);
;         sconv4(rowx, t4, x0, x1, x2, xb, px);
;         float zz[4];
; #pragma unroll
;         for (int j = 0; j < 4; ++j) zz[j] = px[j] * (acc[I][4 * rq + j] * invn0 + pv[j] * d0);
;         uint2 ov; ov.x = pack2(zz[0], zz[1]); ov.y = pack2(zz[2], zz[3]);
;         *(uint2*)(U + (bt * 64 + a) * 136 + bq) = ov;
;       }
	v_fmac_f32_e32 v176, v238, v22
	v_fmac_f32_e32 v177, v238, v23
	v_and_b32_e32 v168, 0xffff0000, v148
	v_lshlrev_b32_e32 v169, 16, v149
	v_and_b32_e32 v170, 0xffff0000, v149
	v_lshlrev_b32_e32 v171, 16, v150
	v_and_b32_e32 v172, 0xffff0000, v150
	v_lshlrev_b32_e32 v173, 16, v151
	v_mul_f32_e32 v178, v244, v168
	v_fmac_f32_e32 v178, v245, v169
	v_fmac_f32_e32 v178, v246, v170
	v_add_f32_e32 v178, v247, v178
	v_mul_f32_e32 v179, v244, v169
	v_fmac_f32_e32 v179, v245, v170
	v_fmac_f32_e32 v179, v246, v171
	v_add_f32_e32 v179, v247, v179
	v_mul_f32_e32 v180, v244, v170
	v_fmac_f32_e32 v180, v245, v171
	v_fmac_f32_e32 v180, v246, v172
	v_add_f32_e32 v180, v247, v180
	v_mul_f32_e32 v181, v244, v171
	v_fmac_f32_e32 v181, v245, v172
	v_fmac_f32_e32 v181, v246, v173
	v_add_f32_e32 v181, v247, v181
	v_mul_f32_e32 v174, v174, v178
	v_mul_f32_e32 v175, v175, v179
	v_mul_f32_e32 v176, v176, v180
	v_mul_f32_e32 v177, v177, v181
	v_cvt_pk_bf16_f32 v182, v174, v175
	v_cvt_pk_bf16_f32 v183, v176, v177
	ds_write_b64 v235, v[182:183] offset:144
	v_and_b32_e32 v168, 0xffff0000, v152
	v_lshlrev_b32_e32 v169, 16, v153
	v_and_b32_e32 v170, 0xffff0000, v153
	v_lshlrev_b32_e32 v171, 16, v154
	v_and_b32_e32 v172, 0xffff0000, v154
	v_lshlrev_b32_e32 v173, 16, v155
	v_mul_f32_e32 v174, v240, v168
	v_fmac_f32_e32 v174, v241, v169
	v_fmac_f32_e32 v174, v242, v170
	v_add_f32_e32 v174, v243, v174
	v_mul_f32_e32 v175, v240, v169
	v_fmac_f32_e32 v175, v241, v170
	v_fmac_f32_e32 v175, v242, v171
	v_add_f32_e32 v175, v243, v175
	v_mul_f32_e32 v176, v240, v170
	v_fmac_f32_e32 v176, v241, v171
	v_fmac_f32_e32 v176, v242, v172
	v_add_f32_e32 v176, v243, v176
	v_mul_f32_e32 v177, v240, v171
	v_fmac_f32_e32 v177, v241, v172
	v_fmac_f32_e32 v177, v242, v173
	v_add_f32_e32 v177, v243, v177
	v_mul_f32_e32 v174, v239, v174
	v_mul_f32_e32 v175, v239, v175
	v_mul_f32_e32 v176, v239, v176
	v_mul_f32_e32 v177, v239, v177
	v_fmac_f32_e32 v174, v238, v24
	v_fmac_f32_e32 v175, v238, v25
	v_fmac_f32_e32 v176, v238, v26
	v_fmac_f32_e32 v177, v238, v27
	v_and_b32_e32 v168, 0xffff0000, v156
	v_lshlrev_b32_e32 v169, 16, v157
	v_and_b32_e32 v170, 0xffff0000, v157
	v_lshlrev_b32_e32 v171, 16, v158
	v_and_b32_e32 v172, 0xffff0000, v158
	v_lshlrev_b32_e32 v173, 16, v159
	v_mul_f32_e32 v178, v244, v168
	v_fmac_f32_e32 v178, v245, v169
	v_fmac_f32_e32 v178, v246, v170
	v_add_f32_e32 v178, v247, v178
	v_mul_f32_e32 v179, v244, v169
	v_fmac_f32_e32 v179, v245, v170
	v_fmac_f32_e32 v179, v246, v171
	v_add_f32_e32 v179, v247, v179
	v_mul_f32_e32 v180, v244, v170
	v_fmac_f32_e32 v180, v245, v171
	v_fmac_f32_e32 v180, v246, v172
	v_add_f32_e32 v180, v247, v180
	v_mul_f32_e32 v181, v244, v171
	v_fmac_f32_e32 v181, v245, v172
	v_fmac_f32_e32 v181, v246, v173
	v_add_f32_e32 v181, v247, v181
	v_mul_f32_e32 v174, v174, v178
	v_mul_f32_e32 v175, v175, v179
	v_mul_f32_e32 v176, v176, v180
	v_mul_f32_e32 v177, v177, v181
	v_cvt_pk_bf16_f32 v182, v174, v175
	v_cvt_pk_bf16_f32 v183, v176, v177
	ds_write_b64 v235, v[182:183] offset:160
	v_and_b32_e32 v168, 0xffff0000, v160
	v_lshlrev_b32_e32 v169, 16, v161
	v_and_b32_e32 v170, 0xffff0000, v161
	v_lshlrev_b32_e32 v171, 16, v162
	v_and_b32_e32 v172, 0xffff0000, v162
	v_lshlrev_b32_e32 v173, 16, v163
	v_mul_f32_e32 v174, v240, v168
	v_fmac_f32_e32 v174, v241, v169
	v_fmac_f32_e32 v174, v242, v170
	v_add_f32_e32 v174, v243, v174
	v_mul_f32_e32 v175, v240, v169
	v_fmac_f32_e32 v175, v241, v170
	v_fmac_f32_e32 v175, v242, v171
	v_add_f32_e32 v175, v243, v175
	v_mul_f32_e32 v176, v240, v170
	v_fmac_f32_e32 v176, v241, v171
	v_fmac_f32_e32 v176, v242, v172
	v_add_f32_e32 v176, v243, v176
	v_mul_f32_e32 v177, v240, v171
	v_fmac_f32_e32 v177, v241, v172
	v_fmac_f32_e32 v177, v242, v173
	v_add_f32_e32 v177, v243, v177
	v_mul_f32_e32 v174, v239, v174
	v_mul_f32_e32 v175, v239, v175
	v_mul_f32_e32 v176, v239, v176
	v_mul_f32_e32 v177, v239, v177
	v_fmac_f32_e32 v174, v238, v28
	v_fmac_f32_e32 v175, v238, v29
	v_fmac_f32_e32 v176, v238, v30
	v_fmac_f32_e32 v177, v238, v31
	v_and_b32_e32 v168, 0xffff0000, v164
	v_lshlrev_b32_e32 v169, 16, v165
	v_and_b32_e32 v170, 0xffff0000, v165
	v_lshlrev_b32_e32 v171, 16, v166
	v_and_b32_e32 v172, 0xffff0000, v166
	v_lshlrev_b32_e32 v173, 16, v167
	v_mul_f32_e32 v178, v244, v168
	v_fmac_f32_e32 v178, v245, v169
	v_fmac_f32_e32 v178, v246, v170
	v_add_f32_e32 v178, v247, v178
	v_mul_f32_e32 v179, v244, v169
	v_fmac_f32_e32 v179, v245, v170
	v_fmac_f32_e32 v179, v246, v171
	v_add_f32_e32 v179, v247, v179
	v_mul_f32_e32 v180, v244, v170
	v_fmac_f32_e32 v180, v245, v171
	v_fmac_f32_e32 v180, v246, v172
	v_add_f32_e32 v180, v247, v180
	v_mul_f32_e32 v181, v244, v171
	v_fmac_f32_e32 v181, v245, v172
	v_fmac_f32_e32 v181, v246, v173
	v_add_f32_e32 v181, v247, v181
	v_mul_f32_e32 v174, v174, v178
	v_mul_f32_e32 v175, v175, v179
	v_mul_f32_e32 v176, v176, v180
	v_mul_f32_e32 v177, v177, v181
	v_cvt_pk_bf16_f32 v182, v174, v175
	v_cvt_pk_bf16_f32 v183, v176, v177
	ds_write_b64 v235, v[182:183] offset:176
	s_waitcnt vmcnt(0)
; DI void hyena_item(const P& p, int l, int c, char* smem) {
;     ...
;   if (cwv) {
;     const float d0 = p.fbias[(size_t)(l * 2 + 0) * 512 + c];
;     const float v0 = cw[c], v1 = cw[1536 + c], v2 = cw[3072 + c], vb = cbias[c];
;     const float x0 = cw[512 + c], x1 = cw[1536 + 512 + c], x2 = cw[3072 + 512 + c], xb = cbias[512 + c];
;     const u16* rowv = p.hyT + (size_t)c * HYP + bt * SEQ;
;     const u16* rowx = p.hyT + (size_t)(512 + c) * HYP + bt * SEQ;
; #pragma unroll
;     for (int I = 0; I < 4; ++I)
; #pragma unroll
;       for (int rq = 0; rq < 4; ++rq) {
;         const int bq = 32 * I + 8 * rq + 4 * g;
;         const int t4 = 128 * a + bq;
;         float pv[4], px[4];
;         sconv4(rowv, t4, v0, v1, v2, vb, pv);
;         sconv4(rowx, t4, x0, x1, x2, xb, px);
;         float zz[4];
; #pragma unroll
;         for (int j = 0; j < 4; ++j) zz[j] = px[j] * (acc[I][4 * rq + j] * invn0 + pv[j] * d0);
;         uint2 ov; ov.x = pack2(zz[0], zz[1]); ov.y = pack2(zz[2], zz[3]);
;         *(uint2*)(U + (bt * 64 + a) * 136 + bq) = ov;
;       }
	v_and_b32_e32 v168, 0xffff0000, v72
	v_lshlrev_b32_e32 v169, 16, v73
	v_and_b32_e32 v170, 0xffff0000, v73
	v_lshlrev_b32_e32 v171, 16, v74
	v_and_b32_e32 v172, 0xffff0000, v74
	v_lshlrev_b32_e32 v173, 16, v75
	v_mul_f32_e32 v174, v240, v168
	v_fmac_f32_e32 v174, v241, v169
	v_fmac_f32_e32 v174, v242, v170
	v_add_f32_e32 v174, v243, v174
	v_mul_f32_e32 v175, v240, v169
	v_fmac_f32_e32 v175, v241, v170
	v_fmac_f32_e32 v175, v242, v171
	v_add_f32_e32 v175, v243, v175
	v_mul_f32_e32 v176, v240, v170
	v_fmac_f32_e32 v176, v241, v171
	v_fmac_f32_e32 v176, v242, v172
	v_add_f32_e32 v176, v243, v176
	v_mul_f32_e32 v177, v240, v171
	v_fmac_f32_e32 v177, v241, v172
	v_fmac_f32_e32 v177, v242, v173
	v_add_f32_e32 v177, v243, v177
	v_mul_f32_e32 v174, v239, v174
	v_mul_f32_e32 v175, v239, v175
	v_mul_f32_e32 v176, v239, v176
	v_mul_f32_e32 v177, v239, v177
	v_fmac_f32_e32 v174, v238, v0
	v_fmac_f32_e32 v175, v238, v1
	v_fmac_f32_e32 v176, v238, v2
	v_fmac_f32_e32 v177, v238, v3
	v_and_b32_e32 v168, 0xffff0000, v76
	v_lshlrev_b32_e32 v169, 16, v77
	v_and_b32_e32 v170, 0xffff0000, v77
	v_lshlrev_b32_e32 v171, 16, v78
	v_and_b32_e32 v172, 0xffff0000, v78
	v_lshlrev_b32_e32 v173, 16, v79
	v_mul_f32_e32 v178, v244, v168
	v_fmac_f32_e32 v178, v245, v169
	v_fmac_f32_e32 v178, v246, v170
	v_add_f32_e32 v178, v247, v178
	v_mul_f32_e32 v179, v244, v169
	v_fmac_f32_e32 v179, v245, v170
	v_fmac_f32_e32 v179, v246, v171
	v_add_f32_e32 v179, v247, v179
	v_mul_f32_e32 v180, v244, v170
	v_fmac_f32_e32 v180, v245, v171
	v_fmac_f32_e32 v180, v246, v172
	v_add_f32_e32 v180, v247, v180
	v_mul_f32_e32 v181, v244, v171
	v_fmac_f32_e32 v181, v245, v172
	v_fmac_f32_e32 v181, v246, v173
	v_add_f32_e32 v181, v247, v181
	v_mul_f32_e32 v174, v174, v178
	v_mul_f32_e32 v175, v175, v179
	v_mul_f32_e32 v176, v176, v180
	v_mul_f32_e32 v177, v177, v181
	v_cvt_pk_bf16_f32 v182, v174, v175
	v_cvt_pk_bf16_f32 v183, v176, v177
	ds_write_b64 v235, v[182:183] offset:192
	v_and_b32_e32 v168, 0xffff0000, v80
	v_lshlrev_b32_e32 v169, 16, v81
	v_and_b32_e32 v170, 0xffff0000, v81
	v_lshlrev_b32_e32 v171, 16, v82
	v_and_b32_e32 v172, 0xffff0000, v82
	v_lshlrev_b32_e32 v173, 16, v83
	v_mul_f32_e32 v174, v240, v168
	v_fmac_f32_e32 v174, v241, v169
	v_fmac_f32_e32 v174, v242, v170
	v_add_f32_e32 v174, v243, v174
	v_mul_f32_e32 v175, v240, v169
	v_fmac_f32_e32 v175, v241, v170
	v_fmac_f32_e32 v175, v242, v171
	v_add_f32_e32 v175, v243, v175
	v_mul_f32_e32 v176, v240, v170
	v_fmac_f32_e32 v176, v241, v171
	v_fmac_f32_e32 v176, v242, v172
	v_add_f32_e32 v176, v243, v176
	v_mul_f32_e32 v177, v240, v171
	v_fmac_f32_e32 v177, v241, v172
	v_fmac_f32_e32 v177, v242, v173
	v_add_f32_e32 v177, v243, v177
	v_mul_f32_e32 v174, v239, v174
	v_mul_f32_e32 v175, v239, v175
	v_mul_f32_e32 v176, v239, v176
	v_mul_f32_e32 v177, v239, v177
	v_fmac_f32_e32 v174, v238, v4
	v_fmac_f32_e32 v175, v238, v5
	v_fmac_f32_e32 v176, v238, v6
	v_fmac_f32_e32 v177, v238, v7
	v_and_b32_e32 v168, 0xffff0000, v84
	v_lshlrev_b32_e32 v169, 16, v85
	v_and_b32_e32 v170, 0xffff0000, v85
	v_lshlrev_b32_e32 v171, 16, v86
	v_and_b32_e32 v172, 0xffff0000, v86
	v_lshlrev_b32_e32 v173, 16, v87
	v_mul_f32_e32 v178, v244, v168
	v_fmac_f32_e32 v178, v245, v169
	v_fmac_f32_e32 v178, v246, v170
	v_add_f32_e32 v178, v247, v178
	v_mul_f32_e32 v179, v244, v169
	v_fmac_f32_e32 v179, v245, v170
	v_fmac_f32_e32 v179, v246, v171
	v_add_f32_e32 v179, v247, v179
	v_mul_f32_e32 v180, v244, v170
	v_fmac_f32_e32 v180, v245, v171
	v_fmac_f32_e32 v180, v246, v172
	v_add_f32_e32 v180, v247, v180
	v_mul_f32_e32 v181, v244, v171
	v_fmac_f32_e32 v181, v245, v172
	v_fmac_f32_e32 v181, v246, v173
	v_add_f32_e32 v181, v247, v181
	v_mul_f32_e32 v174, v174, v178
	v_mul_f32_e32 v175, v175, v179
	v_mul_f32_e32 v176, v176, v180
	v_mul_f32_e32 v177, v177, v181
	v_cvt_pk_bf16_f32 v182, v174, v175
	v_cvt_pk_bf16_f32 v183, v176, v177
	ds_write_b64 v235, v[182:183] offset:208
	v_and_b32_e32 v168, 0xffff0000, v88
	v_lshlrev_b32_e32 v169, 16, v89
; DI float bf2f(unsigned v) { return __uint_as_float(v << 16); }
; DI float bflo(unsigned v) { return __uint_as_float(v << 16); }
; DI float bfhi(unsigned v) { return __uint_as_float(v & 0xffff0000u); }
; DI void sconv4(const u16* row, int t4, float w0, float w1, float w2, float bias, float (&o)[4]) {
;   const uint2 v = *(const uint2*)(row + t4);
;   const float x0 = bflo(v.x), x1 = bfhi(v.x), x2 = bflo(v.y), x3 = bfhi(v.y);
;   const float xm = (t4 > 0) ? bf2f(row[t4 - 1]) : 0.f;
;   const float xp = (t4 + 4 < SEQ) ? bf2f(row[t4 + 4]) : 0.f;
;   o[0] = w0 * xm + w1 * x0 + w2 * x1 + bias;
;   o[1] = w0 * x0 + w1 * x1 + w2 * x2 + bias;
;   o[2] = w0 * x1 + w1 * x2 + w2 * x3 + bias;
;   o[3] = w0 * x2 + w1 * x3 + w2 * xp + bias;
; }
; DI void hyena_item(const P& p, int l, int c, char* smem) {
;     ...
;   if (cwv) {
;     const float d0 = p.fbias[(size_t)(l * 2 + 0) * 512 + c];
;     const float v0 = cw[c], v1 = cw[1536 + c], v2 = cw[3072 + c], vb = cbias[c];
;     const float x0 = cw[512 + c], x1 = cw[1536 + 512 + c], x2 = cw[3072 + 512 + c], xb = cbias[512 + c];
;     const u16* rowv = p.hyT + (size_t)c * HYP + bt * SEQ;
;     const u16* rowx = p.hyT + (size_t)(512 + c) * HYP + bt * SEQ;
; #pragma unroll
;     for (int I = 0; I < 4; ++I)
; #pragma unroll
;       for (int rq = 0; rq < 4; ++rq) {
;         const int bq = 32 * I + 8 * rq + 4 * g;
;         const int t4 = 128 * a + bq;
;         float pv[4], px[4];
;         sconv4(rowv, t4, v0, v1, v2, vb, pv);
;         sconv4(rowx, t4, x0, x1, x2, xb, px);
;         float zz[4];
; #pragma unroll
;         for (int j = 0; j < 4; ++j) zz[j] = px[j] * (acc[I][4 * rq + j] * invn0 + pv[j] * d0);
;         uint2 ov; ov.x = pack2(zz[0], zz[1]); ov.y = pack2(zz[2], zz[3]);
;         *(uint2*)(U + (bt * 64 + a) * 136 + bq) = ov;
;       }
	v_and_b32_e32 v170, 0xffff0000, v89
	v_lshlrev_b32_e32 v171, 16, v90
	v_and_b32_e32 v172, 0xffff0000, v90
	v_lshlrev_b32_e32 v173, 16, v91
	v_mul_f32_e32 v174, v240, v168
	v_fmac_f32_e32 v174, v241, v169
	v_fmac_f32_e32 v174, v242, v170
	v_add_f32_e32 v174, v243, v174
	v_mul_f32_e32 v175, v240, v169
	v_fmac_f32_e32 v175, v241, v170
	v_fmac_f32_e32 v175, v242, v171
	v_add_f32_e32 v175, v243, v175
	v_mul_f32_e32 v176, v240, v170
	v_fmac_f32_e32 v176, v241, v171
	v_fmac_f32_e32 v176, v242, v172
	v_add_f32_e32 v176, v243, v176
	v_mul_f32_e32 v177, v240, v171
	v_fmac_f32_e32 v177, v241, v172
	v_fmac_f32_e32 v177, v242, v173
	v_add_f32_e32 v177, v243, v177
	v_mul_f32_e32 v174, v239, v174
	v_mul_f32_e32 v175, v239, v175
	v_mul_f32_e32 v176, v239, v176
	v_mul_f32_e32 v177, v239, v177
	v_fmac_f32_e32 v174, v238, v8
	v_fmac_f32_e32 v175, v238, v9
	v_fmac_f32_e32 v176, v238, v10
	v_fmac_f32_e32 v177, v238, v11
	v_and_b32_e32 v168, 0xffff0000, v92
	v_lshlrev_b32_e32 v169, 16, v93
	v_and_b32_e32 v170, 0xffff0000, v93
	v_lshlrev_b32_e32 v171, 16, v94
	v_and_b32_e32 v172, 0xffff0000, v94
	v_lshlrev_b32_e32 v173, 16, v95
	v_mul_f32_e32 v178, v244, v168
	v_fmac_f32_e32 v178, v245, v169
	v_fmac_f32_e32 v178, v246, v170
	v_add_f32_e32 v178, v247, v178
	v_mul_f32_e32 v179, v244, v169
	v_fmac_f32_e32 v179, v245, v170
	v_fmac_f32_e32 v179, v246, v171
	v_add_f32_e32 v179, v247, v179
	v_mul_f32_e32 v180, v244, v170
	v_fmac_f32_e32 v180, v245, v171
	v_fmac_f32_e32 v180, v246, v172
	v_add_f32_e32 v180, v247, v180
	v_mul_f32_e32 v181, v244, v171
	v_fmac_f32_e32 v181, v245, v172
	v_fmac_f32_e32 v181, v246, v173
	v_add_f32_e32 v181, v247, v181
	v_mul_f32_e32 v174, v174, v178
	v_mul_f32_e32 v175, v175, v179
	v_mul_f32_e32 v176, v176, v180
	v_mul_f32_e32 v177, v177, v181
	v_cvt_pk_bf16_f32 v182, v174, v175
	v_cvt_pk_bf16_f32 v183, v176, v177
	ds_write_b64 v235, v[182:183] offset:224
	v_cmp_ne_u32_e32 vcc, 0x1f84, v233
	s_nop 1
	v_and_b32_e32 v168, 0xffff0000, v96
	v_lshlrev_b32_e32 v169, 16, v97
	v_and_b32_e32 v170, 0xffff0000, v97
	v_lshlrev_b32_e32 v171, 16, v98
	v_and_b32_e32 v172, 0xffff0000, v98
	v_lshlrev_b32_e32 v173, 16, v99
	v_cndmask_b32_e32 v173, 0, v173, vcc
	v_mul_f32_e32 v174, v240, v168
	v_fmac_f32_e32 v174, v241, v169
	v_fmac_f32_e32 v174, v242, v170
	v_add_f32_e32 v174, v243, v174
	v_mul_f32_e32 v175, v240, v169
	v_fmac_f32_e32 v175, v241, v170
	v_fmac_f32_e32 v175, v242, v171
	v_add_f32_e32 v175, v243, v175
	v_mul_f32_e32 v176, v240, v170
	v_fmac_f32_e32 v176, v241, v171
	v_fmac_f32_e32 v176, v242, v172
	v_add_f32_e32 v176, v243, v176
	v_mul_f32_e32 v177, v240, v171
	v_fmac_f32_e32 v177, v241, v172
	v_fmac_f32_e32 v177, v242, v173
	v_add_f32_e32 v177, v243, v177
	v_mul_f32_e32 v174, v239, v174
	v_mul_f32_e32 v175, v239, v175
	v_mul_f32_e32 v176, v239, v176
	v_mul_f32_e32 v177, v239, v177
	v_fmac_f32_e32 v174, v238, v12
	v_fmac_f32_e32 v175, v238, v13
	v_fmac_f32_e32 v176, v238, v14
	v_fmac_f32_e32 v177, v238, v15
	v_and_b32_e32 v168, 0xffff0000, v100
	v_lshlrev_b32_e32 v169, 16, v101
	v_and_b32_e32 v170, 0xffff0000, v101
	v_lshlrev_b32_e32 v171, 16, v102
	v_and_b32_e32 v172, 0xffff0000, v102
	v_lshlrev_b32_e32 v173, 16, v103
	v_cndmask_b32_e32 v173, 0, v173, vcc
	v_mul_f32_e32 v178, v244, v168
	v_fmac_f32_e32 v178, v245, v169
	v_fmac_f32_e32 v178, v246, v170
	v_add_f32_e32 v178, v247, v178
	v_mul_f32_e32 v179, v244, v169
	v_fmac_f32_e32 v179, v245, v170
	v_fmac_f32_e32 v179, v246, v171
	v_add_f32_e32 v179, v247, v179
	v_mul_f32_e32 v180, v244, v170
	v_fmac_f32_e32 v180, v245, v171
	v_fmac_f32_e32 v180, v246, v172
	v_add_f32_e32 v180, v247, v180
	v_mul_f32_e32 v181, v244, v171
	v_fmac_f32_e32 v181, v245, v172
	v_fmac_f32_e32 v181, v246, v173
	v_add_f32_e32 v181, v247, v181
	v_mul_f32_e32 v174, v174, v178
	v_mul_f32_e32 v175, v175, v179
	v_mul_f32_e32 v176, v176, v180
	v_mul_f32_e32 v177, v177, v181
	v_cvt_pk_bf16_f32 v182, v174, v175
	v_cvt_pk_bf16_f32 v183, v176, v177
	ds_write_b64 v235, v[182:183] offset:240
